# attn_item: PV MFMAs of tile j deferred to top of iteration j+1 (fills K LDS latency); halves are now pure-MFMA / pure-VALU; max chain as 4-way tree after mid barrier
# speedup vs baseline: 1.0426x; 1.0090x over previous
; #define LAS __attribute__((address_space(3)))
; template <bool MASKED>
; __device__ __forceinline__ void attn_step(const bf16x8 (&ka)[2][6], const bf16x8 (&va)[2][4], const bf16x8 (&qf)[6], int nvalid, int lane, f32x16& o0, f32x16& o1, float& mrun, float& lsum) {
;     ...
;     for (int ks = 0; ks < 4; ++ks) { o0 = __builtin_amdgcn_mfma_f32_32x32x16_bf16(va[0][ks], pf[ks], o0, 0, 0, 0); o1 = __builtin_amdgcn_mfma_f32_32x32x16_bf16(va[1][ks], pf[ks], o1, 0, 0, 0); }
; __device__ __forceinline__ void attn_item(const Params& p, int l, LAS unsigned char* lds, int b, int h, int J) {
;     ...
;         if (j < my_nt) {
;             bf16x8 ka[2][6], va[2][4];
; #pragma unroll
;             for (int kb = 0; kb < 2; ++kb)
; #pragma unroll
;                 for (int s = 0; s < 6; ++s) ka[kb][s] = *(const LAS bf16x8*)(cur + rk + kb * 32 * KROW + 32 * s);
; #pragma unroll
;             for (int dvb = 0; dvb < 2; ++dvb)
; #pragma unroll
;                 for (int ks = 0; ks < 4; ++ks) va[dvb][ks] = *(const LAS bf16x8*)(cur + rv + dvb * 32 * VROW + 32 * ks);
;             __builtin_amdgcn_sched_barrier(0);
;             if (j < my_nt - 1) attn_step<false>(ka, va, qf, 64, lane, o0, o1, mrun, lsum); else attn_step<true>(ka, va, qf, 16, lane, o0, o1, mrun, lsum);
.Latt_noe:
	s_cmp_ge_i32 s13, s11
	s_cbranch_scc1 .Latt_skip
	s_bitcmp1_b32 s13, 0
	s_cselect_b32 s14, 0x5800, 0
	s_add_i32 s14, s14, 0
	v_add3_u32 v0, s14, v233, v236
	ds_read_b128 v[186:189], v0
	ds_read_b128 v[182:185], v0 offset:32
	ds_read_b128 v[178:181], v0 offset:64
	ds_read_b128 v[174:177], v0 offset:96
	ds_read_b128 v[170:173], v0 offset:128
	ds_read_b128 v[166:169], v0 offset:160
	ds_read_b128 v[50:53], v0 offset:6656
	ds_read_b128 v[206:209], v0 offset:6688
	ds_read_b128 v[202:205], v0 offset:6720
	ds_read_b128 v[198:201], v0 offset:6752
	ds_read_b128 v[194:197], v0 offset:6784
	ds_read_b128 v[190:193], v0 offset:6816
	s_cmp_eq_u32 s13, 0
	s_cbranch_scc1 .Latt_nopv
	v_mfma_f32_32x32x16_bf16 v[18:33], v[158:161], v[82:85], v[18:33]
	v_mfma_f32_32x32x16_bf16 v[2:17], v[162:165], v[82:85], v[2:17]
	v_mfma_f32_32x32x16_bf16 v[18:33], v[150:153], v[86:89], v[18:33]
	v_mfma_f32_32x32x16_bf16 v[2:17], v[154:157], v[86:89], v[2:17]
	v_mfma_f32_32x32x16_bf16 v[18:33], v[146:149], v[90:93], v[18:33]
	v_mfma_f32_32x32x16_bf16 v[2:17], v[142:145], v[90:93], v[2:17]
	v_mfma_f32_32x32x16_bf16 v[18:33], v[138:141], v[94:97], v[18:33]
	v_mfma_f32_32x32x16_bf16 v[2:17], v[134:137], v[94:97], v[2:17]
.Latt_nopv:
	v_add3_u32 v0, s14, v237, v236
	s_cmp_gt_i32 s13, s10
	s_cbranch_scc1 .Latt_masked
	s_waitcnt lgkmcnt(0)
	v_mfma_f32_32x32x16_bf16 v[66:81], v[186:189], v[110:113], v[34:49]
	v_mfma_f32_32x32x16_bf16 v[66:81], v[182:185], v[114:117], v[66:81]
	v_mfma_f32_32x32x16_bf16 v[50:65], v[50:53], v[110:113], v[34:49]
	v_mfma_f32_32x32x16_bf16 v[66:81], v[178:181], v[118:121], v[66:81]
	ds_read_b128 v[158:161], v0 offset:13312
	ds_read_b128 v[150:153], v0 offset:13344
	ds_read_b128 v[146:149], v0 offset:13376
	ds_read_b128 v[138:141], v0 offset:13408
	ds_read_b128 v[162:165], v0 offset:17920
	ds_read_b128 v[154:157], v0 offset:17952
	ds_read_b128 v[142:145], v0 offset:17984
	ds_read_b128 v[134:137], v0 offset:18016
	v_mfma_f32_32x32x16_bf16 v[50:65], v[206:209], v[114:117], v[50:65]
	v_mfma_f32_32x32x16_bf16 v[66:81], v[174:177], v[122:125], v[66:81]
	v_mfma_f32_32x32x16_bf16 v[50:65], v[202:205], v[118:121], v[50:65]
	v_mfma_f32_32x32x16_bf16 v[66:81], v[170:173], v[126:129], v[66:81]
	v_mfma_f32_32x32x16_bf16 v[50:65], v[198:201], v[122:125], v[50:65]
	v_mfma_f32_32x32x16_bf16 v[66:81], v[166:169], v[130:133], v[66:81]
	v_mfma_f32_32x32x16_bf16 v[50:65], v[194:197], v[126:129], v[50:65]
	v_mfma_f32_32x32x16_bf16 v[50:65], v[190:193], v[130:133], v[50:65]
	s_waitcnt lgkmcnt(0)
	s_barrier
	s_add_i32 s14, s12, 1
	s_cmp_lt_i32 s14, s5
	s_cbranch_scc0 .Latt_nold_main
	global_load_dwordx4 v[98:101], v[242:243], off
	global_load_dwordx4 v[102:105], v[244:245], off
	s_and_saveexec_b64 s[50:51], s[40:41]
	s_cbranch_execz .Latt_ldx_main
	global_load_dwordx4 v[106:109], v[240:241], off

; template <bool MASKED>
; __device__ __forceinline__ void attn_step(const bf16x8 (&ka)[2][6], const bf16x8 (&va)[2][4], const bf16x8 (&qf)[6], int nvalid, int lane, f32x16& o0, f32x16& o1, float& mrun, float& lsum) {
;     ...
;     float mx = fmaxf(fmaxf(s0[0], s0[1]), s0[2]);
; #pragma unroll
;     for (int i = 3; i < 15; i += 2) mx = fmaxf(fmaxf(mx, s0[i]), s0[i + 1]);
;     mx = fmaxf(mx, s0[15]);
; #pragma unroll
;     for (int i = 0; i < 16; i += 2) mx = fmaxf(fmaxf(mx, s1[i]), s1[i + 1]);
;     if (__builtin_amdgcn_ballot_w64(mx > mrun + 8.0f) != 0ull) {
;         mx = fmaxf(mx, shx32(mx, lane));
;         const float mnew = fmaxf(mrun, mx);
;         const float alpha = __builtin_amdgcn_exp2f(mrun - mnew);
;         mrun = mnew; lsum *= alpha;
; #pragma unroll
;         for (int i = 0; i < 16; ++i) { o0[i] *= alpha; o1[i] *= alpha; }
;     }
;     {
;         const f32x2 m2 = {mrun, mrun}; f32x2 acc2 = {0.f, 0.f};
; #pragma unroll
;         for (int i = 0; i < 16; i += 2) {
;             f32x2 a = (f32x2){s0[i], s0[i + 1]} - m2, c = (f32x2){s1[i], s1[i + 1]} - m2;
;             a.x = __builtin_amdgcn_exp2f(a.x); a.y = __builtin_amdgcn_exp2f(a.y); c.x = __builtin_amdgcn_exp2f(c.x); c.y = __builtin_amdgcn_exp2f(c.y);
;             acc2 = acc2 + a; acc2 = acc2 + c;
;             s0[i] = a.x; s0[i + 1] = a.y; s1[i] = c.x; s1[i + 1] = c.y;
;         }
;         lsum += acc2.x + acc2.y;
;     }
;     bf16x8 pf[4];
;     { u32x4 w;
;       w.x = pk2(s0[0], s0[1]); w.y = pk2(s0[2], s0[3]); w.z = pk2(s0[4], s0[5]); w.w = pk2(s0[6], s0[7]); pf[0] = __builtin_bit_cast(bf16x8, w);
;       w.x = pk2(s0[8], s0[9]); w.y = pk2(s0[10], s0[11]); w.z = pk2(s0[12], s0[13]); w.w = pk2(s0[14], s0[15]); pf[1] = __builtin_bit_cast(bf16x8, w);
;       w.x = pk2(s1[0], s1[1]); w.y = pk2(s1[2], s1[3]); w.z = pk2(s1[4], s1[5]); w.w = pk2(s1[6], s1[7]); pf[2] = __builtin_bit_cast(bf16x8, w);
;       w.x = pk2(s1[8], s1[9]); w.y = pk2(s1[10], s1[11]); w.z = pk2(s1[12], s1[13]); w.w = pk2(s1[14], s1[15]); pf[3] = __builtin_bit_cast(bf16x8, w); }
; #pragma unroll
;     for (int ks = 0; ks < 4; ++ks) { o0 = __builtin_amdgcn_mfma_f32_32x32x16_bf16(va[0][ks], pf[ks], o0, 0, 0, 0); o1 = __builtin_amdgcn_mfma_f32_32x32x16_bf16(va[1][ks], pf[ks], o1, 0, 0, 0); }
.Latt_nold_main:
	s_nop 9
	v_max3_f32 v0, v66, v67, v68
	v_max3_f32 v83, v69, v70, v71
	v_max3_f32 v84, v50, v51, v52
	v_max3_f32 v85, v53, v54, v55
	v_max3_f32 v0, v0, v72, v73
	v_max3_f32 v83, v83, v74, v75
	v_max3_f32 v84, v84, v56, v57
	v_max3_f32 v85, v85, v58, v59
	v_max3_f32 v0, v0, v76, v77
	v_max3_f32 v83, v83, v78, v79
	v_max3_f32 v84, v84, v60, v61
	v_max3_f32 v85, v85, v62, v63
	v_max3_f32 v0, v0, v80, v81
	v_max3_f32 v84, v84, v64, v65
	v_max3_f32 v0, v0, v83, v84
	v_max_f32_e32 v0, v0, v85
	v_cmp_gt_f32_e32 vcc, v0, v212
	s_cbranch_vccz .Latt_softmax
	ds_bpermute_b32 v82, v235, v0
	s_waitcnt lgkmcnt(0)
	v_max3_f32 v82, v0, v82, v213
	v_exp_f32_e64 v84, -v82
	v_add_f32_e32 v250, v250, v82
	v_mov_b32_e32 v212, 0x41000000
	v_mul_f32_e32 v249, v249, v84
	v_pk_mul_f32 v[32:33], v[32:33], v[84:85] op_sel_hi:[1,0]
	v_pk_mul_f32 v[30:31], v[30:31], v[84:85] op_sel_hi:[1,0]
	v_pk_mul_f32 v[28:29], v[28:29], v[84:85] op_sel_hi:[1,0]
	v_pk_mul_f32 v[26:27], v[26:27], v[84:85] op_sel_hi:[1,0]
	v_pk_mul_f32 v[24:25], v[24:25], v[84:85] op_sel_hi:[1,0]
	v_pk_mul_f32 v[22:23], v[22:23], v[84:85] op_sel_hi:[1,0]
	v_pk_mul_f32 v[20:21], v[20:21], v[84:85] op_sel_hi:[1,0]
	v_pk_mul_f32 v[18:19], v[18:19], v[84:85] op_sel_hi:[1,0]
	v_pk_mul_f32 v[16:17], v[16:17], v[84:85] op_sel_hi:[1,0]
	v_pk_mul_f32 v[14:15], v[14:15], v[84:85] op_sel_hi:[1,0]
	v_pk_mul_f32 v[12:13], v[12:13], v[84:85] op_sel_hi:[1,0]
	v_pk_mul_f32 v[10:11], v[10:11], v[84:85] op_sel_hi:[1,0]
	v_pk_mul_f32 v[8:9], v[8:9], v[84:85] op_sel_hi:[1,0]
	v_pk_mul_f32 v[6:7], v[6:7], v[84:85] op_sel_hi:[1,0]
	v_pk_mul_f32 v[4:5], v[4:5], v[84:85] op_sel_hi:[1,0]
	v_pk_mul_f32 v[2:3], v[2:3], v[84:85] op_sel_hi:[1,0]
	v_mov_b32_e32 v213, 0
	v_xor_b32_e32 v34, 0x80000000, v250
	v_sub_f32_e32 v66, v66, v82
	v_sub_f32_e32 v67, v67, v82
	v_sub_f32_e32 v68, v68, v82
	v_sub_f32_e32 v69, v69, v82
	v_sub_f32_e32 v70, v70, v82
	v_sub_f32_e32 v71, v71, v82
	v_sub_f32_e32 v72, v72, v82
	v_sub_f32_e32 v73, v73, v82
	v_sub_f32_e32 v74, v74, v82
	v_sub_f32_e32 v75, v75, v82
	v_sub_f32_e32 v76, v76, v82
	v_sub_f32_e32 v77, v77, v82
	v_sub_f32_e32 v78, v78, v82
	v_sub_f32_e32 v79, v79, v82
	v_sub_f32_e32 v80, v80, v82
	v_sub_f32_e32 v81, v81, v82
	v_sub_f32_e32 v50, v50, v82
	v_sub_f32_e32 v51, v51, v82
	v_sub_f32_e32 v52, v52, v82
	v_sub_f32_e32 v53, v53, v82
	v_sub_f32_e32 v54, v54, v82
	v_sub_f32_e32 v55, v55, v82
	v_sub_f32_e32 v56, v56, v82
	v_sub_f32_e32 v57, v57, v82
	v_sub_f32_e32 v58, v58, v82
	v_sub_f32_e32 v59, v59, v82
	v_sub_f32_e32 v60, v60, v82
	v_sub_f32_e32 v61, v61, v82
	v_sub_f32_e32 v62, v62, v82
	v_sub_f32_e32 v63, v63, v82
	v_sub_f32_e32 v64, v64, v82
	v_sub_f32_e32 v65, v65, v82
	v_mov_b32_e32 v35, v34
	v_mov_b32_e32 v36, v34
	v_mov_b32_e32 v37, v34
	v_mov_b32_e32 v38, v34
	v_mov_b32_e32 v39, v34
	v_mov_b32_e32 v40, v34
	v_mov_b32_e32 v41, v34
	v_mov_b32_e32 v42, v34
	v_mov_b32_e32 v43, v34
	v_mov_b32_e32 v44, v34
	v_mov_b32_e32 v45, v34
	v_mov_b32_e32 v46, v34
	v_mov_b32_e32 v47, v34
	v_mov_b32_e32 v48, v34
	v_mov_b32_e32 v49, v34
.Latt_softmax:
	v_exp_f32_e32 v66, v66
	v_exp_f32_e32 v67, v67
	v_exp_f32_e32 v68, v68
	v_exp_f32_e32 v69, v69
	v_exp_f32_e32 v70, v70
	v_exp_f32_e32 v71, v71
	v_cvt_pk_bf16_f32 v82, v66, v67
	v_exp_f32_e32 v72, v72
	v_cvt_pk_bf16_f32 v83, v68, v69
	v_exp_f32_e32 v73, v73
	v_cvt_pk_bf16_f32 v84, v70, v71
	v_add_f32_e32 v190, v66, v67
	v_add_f32_e32 v191, v68, v69
	v_cvt_pk_bf16_f32 v85, v72, v73
	v_exp_f32_e32 v74, v74
	v_exp_f32_e32 v75, v75
	v_exp_f32_e32 v76, v76
	v_add_f32_e32 v190, v190, v70
	v_add_f32_e32 v191, v191, v71
	v_exp_f32_e32 v77, v77
	v_exp_f32_e32 v78, v78
	v_add_f32_e32 v190, v190, v72
	v_add_f32_e32 v191, v191, v73
	v_exp_f32_e32 v79, v79
	v_cvt_pk_bf16_f32 v86, v74, v75
	v_exp_f32_e32 v80, v80
	v_cvt_pk_bf16_f32 v87, v76, v77
	v_exp_f32_e32 v81, v81
	v_cvt_pk_bf16_f32 v88, v78, v79
	v_add_f32_e32 v190, v190, v74
	v_add_f32_e32 v191, v191, v75
	v_cvt_pk_bf16_f32 v89, v80, v81
	v_exp_f32_e32 v50, v50
	v_exp_f32_e32 v51, v51
	v_exp_f32_e32 v52, v52
	v_add_f32_e32 v190, v190, v76
	v_add_f32_e32 v191, v191, v77
	v_exp_f32_e32 v53, v53
	v_exp_f32_e32 v54, v54
	v_add_f32_e32 v190, v190, v78
	v_add_f32_e32 v191, v191, v79
	v_exp_f32_e32 v55, v55
	v_cvt_pk_bf16_f32 v90, v50, v51
	v_exp_f32_e32 v56, v56
	v_cvt_pk_bf16_f32 v91, v52, v53
	v_exp_f32_e32 v57, v57
	v_cvt_pk_bf16_f32 v92, v54, v55
	v_add_f32_e32 v190, v190, v80
	v_add_f32_e32 v191, v191, v81
	v_cvt_pk_bf16_f32 v93, v56, v57
	v_exp_f32_e32 v58, v58
	v_exp_f32_e32 v59, v59
	v_exp_f32_e32 v60, v60
	v_add_f32_e32 v190, v190, v50
	v_add_f32_e32 v191, v191, v51
	v_exp_f32_e32 v61, v61
	v_exp_f32_e32 v62, v62
	v_add_f32_e32 v190, v190, v52
	v_add_f32_e32 v191, v191, v53
	v_exp_f32_e32 v63, v63
	v_cvt_pk_bf16_f32 v94, v58, v59
	v_exp_f32_e32 v64, v64
	v_cvt_pk_bf16_f32 v95, v60, v61
	v_exp_f32_e32 v65, v65
	v_cvt_pk_bf16_f32 v96, v62, v63
	v_add_f32_e32 v190, v190, v54
	v_add_f32_e32 v191, v191, v55
	v_cvt_pk_bf16_f32 v97, v64, v65
	v_add_f32_e32 v190, v190, v56
	v_add_f32_e32 v191, v191, v57
	v_add_f32_e32 v190, v190, v58
	v_add_f32_e32 v191, v191, v59
	v_add_f32_e32 v190, v190, v60
	v_add_f32_e32 v191, v191, v61
	v_add_f32_e32 v190, v190, v62
	v_add_f32_e32 v191, v191, v63
	v_add_f32_e32 v190, v190, v64
	v_add_f32_e32 v191, v191, v65
	v_add_f32_e32 v190, v190, v191
	v_add_f32_e32 v249, v249, v190
	v_mov_b64_e32 v[200:201], v[216:217]
	s_branch .Latt_end
.Latt_masked:
	v_add_f32_e32 v212, 0x41000000, v250
	ds_read_b128 v[158:161], v0 offset:13312
	ds_read_b128 v[150:153], v0 offset:13344
	ds_read_b128 v[146:149], v0 offset:13376
	ds_read_b128 v[138:141], v0 offset:13408
	ds_read_b128 v[162:165], v0 offset:17920
	ds_read_b128 v[154:157], v0 offset:17952
	ds_read_b128 v[142:145], v0 offset:17984
	ds_read_b128 v[134:137], v0 offset:18016
	s_waitcnt lgkmcnt(0)
	s_barrier
	s_add_i32 s14, s12, 1
	s_cmp_lt_i32 s14, s5
	s_cbranch_scc0 .Latt_nold_mask
	global_load_dwordx4 v[98:101], v[242:243], off
	global_load_dwordx4 v[102:105], v[244:245], off
	s_and_saveexec_b64 s[50:51], s[40:41]
	s_cbranch_execz .Latt_ldx_mask
	global_load_dwordx4 v[106:109], v[240:241], off
